# attention: redundant end-of-unit s_barrier removed (epilogue LDS is wave-private; slot reuse is fenced by the loop's latch barriers)
# speedup vs baseline: 1.0072x; 1.0011x over previous
; #define LAS __attribute__((address_space(3)))
; __device__ __forceinline__ bf16_t f2bf(float f) { return (bf16_t)(cvtpk(f, 0.f) & 0xffffu); }
; __device__ __forceinline__ float frcp(float x) { return __builtin_amdgcn_rcpf(x); }
; __device__ __forceinline__ int crow(int r, int hi) { return (r & 3) + 8 * (r >> 2) + 4 * hi; }
; __device__ __forceinline__ void attn_unit(LAS char* lds, const bf16_t* Qp, const bf16_t* KVp, const bf16_t* KRp, int ntiles, bf16_t* Yp, bool dry) {
;     ...
;     lsum += __shfl_xor(lsum, 32);
;     if (hi == 0) wsf[r32] = frcp(lsum);
;     asm volatile("s_waitcnt lgkmcnt(0)" ::: "memory");
;     LAS char* ost = lds + A_OST + wid * (32 * A_OP);
; #pragma unroll
;     for (int k = 0; k < 4; ++k) { const f32x4 a = *(const LAS f32x4*)(wsf + 8 * k + 4 * hi);
; #pragma unroll
;         for (int j = 0; j < 4; ++j) { const int r = 4 * k + j; LAS bf16_t* op = (LAS bf16_t*)(ost + crow(r, hi) * A_OP) + r32;
;             op[0] = f2bf(o0[r] * a[j]); op[32] = f2bf(o1[r] * a[j]); } }
;     asm volatile("s_waitcnt lgkmcnt(0)" ::: "memory");
; #pragma unroll
;     for (int i = 0; i < 4; ++i) { const int id = lane + 64 * i, row = id >> 3, ch = id & 7;
;         const u32x4 ov = *(const LAS u32x4*)(ost + row * A_OP + ch * 16);
;         bf16_t* yp = Yp + (size_t)(wid * 32 + row) * ZP + ch * 8;
.Lepi_gates_done:
	s_waitcnt lgkmcnt(1)
	v_lshlrev_b32_e32 v0, 1, v198
	v_mul_u32_u24_e32 v6, 0x240, v197
	v_add3_u32 v0, s2, v0, v6
	s_waitcnt lgkmcnt(0)
	v_mul_f32_e32 v6, v34, v2
	v_mul_f32_e32 v2, v50, v2
	v_cvt_pk_bf16_f32 v2, v2, s0
	ds_write_b16 v0, v2 offset:64
	v_mul_f32_e32 v2, v35, v3
	v_cvt_pk_bf16_f32 v2, v2, s0
	ds_write_b16 v0, v2 offset:144
	v_mul_f32_e32 v2, v51, v3
	v_cvt_pk_bf16_f32 v2, v2, s0
	ds_write_b16 v0, v2 offset:208
	v_mul_f32_e32 v2, v36, v4
	v_cvt_pk_bf16_f32 v2, v2, s0
	ds_write_b16 v0, v2 offset:288
	v_mul_f32_e32 v2, v52, v4
	v_cvt_pk_bf16_f32 v2, v2, s0
	ds_write_b16 v0, v2 offset:352
	v_mul_f32_e32 v2, v37, v5
	v_cvt_pk_bf16_f32 v2, v2, s0
	ds_write_b16 v0, v2 offset:432
	v_mul_f32_e32 v2, v53, v5
	v_cvt_pk_bf16_f32 v6, v6, s0
	v_cvt_pk_bf16_f32 v2, v2, s0
	ds_write_b16 v0, v6
	ds_write_b16 v0, v2 offset:496
	ds_read_b128 v[2:5], v199 offset:32
	s_waitcnt lgkmcnt(0)
	v_mul_f32_e32 v6, v38, v2
	v_mul_f32_e32 v2, v54, v2
	v_cvt_pk_bf16_f32 v2, v2, s0
	ds_write_b16 v0, v2 offset:1216
	v_mul_f32_e32 v2, v39, v3
	v_cvt_pk_bf16_f32 v2, v2, s0
	ds_write_b16 v0, v2 offset:1296
	v_mul_f32_e32 v2, v55, v3
	v_cvt_pk_bf16_f32 v2, v2, s0
	ds_write_b16 v0, v2 offset:1360
	v_mul_f32_e32 v2, v40, v4
	v_cvt_pk_bf16_f32 v2, v2, s0
	ds_write_b16 v0, v2 offset:1440
	v_mul_f32_e32 v2, v56, v4
	v_cvt_pk_bf16_f32 v2, v2, s0
	ds_write_b16 v0, v2 offset:1504
	v_mul_f32_e32 v2, v41, v5
	v_cvt_pk_bf16_f32 v2, v2, s0
	ds_write_b16 v0, v2 offset:1584
	v_mul_f32_e32 v2, v57, v5
	v_cvt_pk_bf16_f32 v6, v6, s0
	v_cvt_pk_bf16_f32 v2, v2, s0
	ds_write_b16 v0, v6 offset:1152
	ds_write_b16 v0, v2 offset:1648
	ds_read_b128 v[2:5], v199 offset:64
	s_waitcnt lgkmcnt(0)
	v_mul_f32_e32 v6, v42, v2
	v_mul_f32_e32 v2, v58, v2
	v_cvt_pk_bf16_f32 v2, v2, s0
	ds_write_b16 v0, v2 offset:2368
	v_mul_f32_e32 v2, v43, v3
	v_cvt_pk_bf16_f32 v2, v2, s0
	ds_write_b16 v0, v2 offset:2448
	v_mul_f32_e32 v2, v59, v3
	v_cvt_pk_bf16_f32 v2, v2, s0
	ds_write_b16 v0, v2 offset:2512
	v_mul_f32_e32 v2, v44, v4
	v_cvt_pk_bf16_f32 v2, v2, s0
	ds_write_b16 v0, v2 offset:2592
	v_mul_f32_e32 v2, v60, v4
	v_cvt_pk_bf16_f32 v2, v2, s0
	ds_write_b16 v0, v2 offset:2656
	v_mul_f32_e32 v2, v45, v5
	v_cvt_pk_bf16_f32 v2, v2, s0
	ds_write_b16 v0, v2 offset:2736
	v_mul_f32_e32 v2, v61, v5
	v_cvt_pk_bf16_f32 v6, v6, s0
	v_cvt_pk_bf16_f32 v2, v2, s0
	ds_write_b16 v0, v6 offset:2304
	ds_write_b16 v0, v2 offset:2800
	ds_read_b128 v[2:5], v199 offset:96
	s_waitcnt lgkmcnt(0)
	v_mul_f32_e32 v6, v46, v2
	v_mul_f32_e32 v2, v62, v2
	v_cvt_pk_bf16_f32 v2, v2, s0
	ds_write_b16 v0, v2 offset:3520
	v_mul_f32_e32 v2, v47, v3
	v_cvt_pk_bf16_f32 v2, v2, s0
	ds_write_b16 v0, v2 offset:3600
	v_mul_f32_e32 v2, v63, v3
	v_cvt_pk_bf16_f32 v2, v2, s0
	ds_write_b16 v0, v2 offset:3664
	v_mul_f32_e32 v2, v48, v4
	v_cvt_pk_bf16_f32 v2, v2, s0
	ds_write_b16 v0, v2 offset:3744
	v_mul_f32_e32 v2, v64, v4
	v_cvt_pk_bf16_f32 v2, v2, s0
	ds_write_b16 v0, v2 offset:3808
	v_mul_f32_e32 v2, v49, v5
	v_cvt_pk_bf16_f32 v2, v2, s0
	ds_write_b16 v0, v2 offset:3888
	v_mul_f32_e32 v2, v65, v5
	v_cvt_pk_bf16_f32 v6, v6, s0
	v_cvt_pk_bf16_f32 v2, v2, s0
	ds_write_b16 v0, v6 offset:3456
	ds_write_b16 v0, v2 offset:3952
	v_lshlrev_b32_e32 v0, 1, v196
	v_lshl_add_u64 v[2:3], s[0:1], 0, v[0:1]
	s_mov_b64 s[0:1], 0x1000
	v_lshrrev_b32_e32 v0, 3, v191
	v_lshl_add_u64 v[2:3], v[2:3], 0, s[0:1]
	v_or_b32_e32 v18, s24, v0
	s_waitcnt lgkmcnt(0)
	v_mad_i64_i32 v[12:13], s[0:1], v18, s13, v[2:3]
	s_nop 0
	v_mul_u32_u24_e32 v0, 0x90, v0
	v_add3_u32 v0, s2, v188, v0
	ds_read_b128 v[4:7], v0
	s_waitcnt lgkmcnt(0)
	v_lshlrev_b32_e32 v14, 16, v4
	v_and_b32_e32 v15, 0xffff0000, v4
	s_waitcnt vmcnt(0)
; #define LAS __attribute__((address_space(3)))
; __device__ __forceinline__ unsigned cvtpk(float lo, float hi) { f32x2 v = {lo, hi}; bf16x2_t b = __builtin_convertvector(v, bf16x2_t); return __builtin_bit_cast(unsigned, b); }
; __device__ __forceinline__ float bflo(unsigned u) { return __uint_as_float(u << 16); }
; __device__ __forceinline__ float bfhi(unsigned u) { return __uint_as_float(u & 0xffff0000u); }
; __device__ __forceinline__ void attn_unit(LAS char* lds, const bf16_t* Qp, const bf16_t* KVp, const bf16_t* KRp, int ntiles, bf16_t* Yp, bool dry) {
;     ...
;     for (int i = 0; i < 4; ++i) { const int id = lane + 64 * i, row = id >> 3, ch = id & 7;
;         const u32x4 ov = *(const LAS u32x4*)(ost + row * A_OP + ch * 16);
;         bf16_t* yp = Yp + (size_t)(wid * 32 + row) * ZP + ch * 8;
;         if (!dry) { const u32x4 gv = *(const u32x4*)yp; u32x4 w;
;             w.x = cvtpk(bflo(ov.x) * bflo(gv.x), bfhi(ov.x) * bfhi(gv.x)); w.y = cvtpk(bflo(ov.y) * bflo(gv.y), bfhi(ov.y) * bfhi(gv.y));
;             w.z = cvtpk(bflo(ov.z) * bflo(gv.z), bfhi(ov.z) * bfhi(gv.z)); w.w = cvtpk(bflo(ov.w) * bflo(gv.w), bfhi(ov.w) * bfhi(gv.w));
;             *(u32x4*)yp = w; } }
;     __syncthreads();
; }
	v_mov_b64_e32 v[8:9], v[130:131]
	v_mov_b64_e32 v[10:11], v[132:133]
	v_lshlrev_b32_e32 v16, 16, v8
	v_and_b32_e32 v17, 0xffff0000, v8
	v_pk_mul_f32 v[14:15], v[14:15], v[16:17]
	v_lshlrev_b32_e32 v8, 16, v9
	v_cvt_pk_bf16_f32 v4, v14, v15
	v_lshlrev_b32_e32 v14, 16, v5
	v_and_b32_e32 v15, 0xffff0000, v5
	v_and_b32_e32 v9, 0xffff0000, v9
	v_pk_mul_f32 v[8:9], v[14:15], v[8:9]
	v_lshlrev_b32_e32 v14, 16, v10
	v_cvt_pk_bf16_f32 v5, v8, v9
	v_lshlrev_b32_e32 v8, 16, v6
	v_and_b32_e32 v9, 0xffff0000, v6
	v_and_b32_e32 v15, 0xffff0000, v10
	v_pk_mul_f32 v[8:9], v[8:9], v[14:15]
	v_lshlrev_b32_e32 v10, 16, v11
	v_cvt_pk_bf16_f32 v6, v8, v9
	v_lshlrev_b32_e32 v8, 16, v7
	v_and_b32_e32 v9, 0xffff0000, v7
	v_and_b32_e32 v11, 0xffff0000, v11
	v_pk_mul_f32 v[8:9], v[8:9], v[10:11]
	s_nop 0
	v_cvt_pk_bf16_f32 v7, v8, v9
	global_store_dwordx4 v[12:13], v[4:7], off
	s_nop 1
	v_or_b32_e32 v4, 8, v18
	v_mad_i64_i32 v[12:13], s[0:1], v4, s13, v[2:3]
	s_nop 0
	ds_read_b128 v[4:7], v0 offset:1152
	s_waitcnt lgkmcnt(0)
	v_lshlrev_b32_e32 v14, 16, v4
	v_and_b32_e32 v15, 0xffff0000, v4
	v_mov_b64_e32 v[8:9], v[134:135]
	v_mov_b64_e32 v[10:11], v[136:137]
	v_lshlrev_b32_e32 v16, 16, v8
	v_and_b32_e32 v17, 0xffff0000, v8
	v_pk_mul_f32 v[14:15], v[14:15], v[16:17]
	v_lshlrev_b32_e32 v8, 16, v9
	v_cvt_pk_bf16_f32 v4, v14, v15
	v_lshlrev_b32_e32 v14, 16, v5
	v_and_b32_e32 v15, 0xffff0000, v5
	v_and_b32_e32 v9, 0xffff0000, v9
	v_pk_mul_f32 v[8:9], v[14:15], v[8:9]
	v_lshlrev_b32_e32 v14, 16, v10
	v_cvt_pk_bf16_f32 v5, v8, v9
	v_lshlrev_b32_e32 v8, 16, v6
	v_and_b32_e32 v9, 0xffff0000, v6
	v_and_b32_e32 v15, 0xffff0000, v10
	v_pk_mul_f32 v[8:9], v[8:9], v[14:15]
	v_lshlrev_b32_e32 v10, 16, v11
	v_cvt_pk_bf16_f32 v6, v8, v9
	v_lshlrev_b32_e32 v8, 16, v7
	v_and_b32_e32 v9, 0xffff0000, v7
	v_and_b32_e32 v11, 0xffff0000, v11
	v_pk_mul_f32 v[8:9], v[8:9], v[10:11]
	s_nop 0
	v_cvt_pk_bf16_f32 v7, v8, v9
	global_store_dwordx4 v[12:13], v[4:7], off
	s_nop 1
	v_or_b32_e32 v4, 16, v18
	v_mad_i64_i32 v[12:13], s[0:1], v4, s13, v[2:3]
	s_nop 0
	ds_read_b128 v[4:7], v0 offset:2304
	s_waitcnt lgkmcnt(0)
	v_lshlrev_b32_e32 v14, 16, v4
	v_and_b32_e32 v15, 0xffff0000, v4
	v_mov_b64_e32 v[8:9], v[138:139]
	v_mov_b64_e32 v[10:11], v[140:141]
	v_lshlrev_b32_e32 v16, 16, v8
	v_and_b32_e32 v17, 0xffff0000, v8
	v_pk_mul_f32 v[14:15], v[14:15], v[16:17]
	v_lshlrev_b32_e32 v8, 16, v9
	v_cvt_pk_bf16_f32 v4, v14, v15
	v_lshlrev_b32_e32 v14, 16, v5
	v_and_b32_e32 v15, 0xffff0000, v5
	v_and_b32_e32 v9, 0xffff0000, v9
	v_pk_mul_f32 v[8:9], v[14:15], v[8:9]
	v_lshlrev_b32_e32 v14, 16, v10
	v_cvt_pk_bf16_f32 v5, v8, v9
	v_lshlrev_b32_e32 v8, 16, v6
	v_and_b32_e32 v9, 0xffff0000, v6
	v_and_b32_e32 v15, 0xffff0000, v10
	v_pk_mul_f32 v[8:9], v[8:9], v[14:15]
	v_lshlrev_b32_e32 v10, 16, v11
	v_cvt_pk_bf16_f32 v6, v8, v9
	v_lshlrev_b32_e32 v8, 16, v7
	v_and_b32_e32 v9, 0xffff0000, v7
	v_and_b32_e32 v11, 0xffff0000, v11
	v_pk_mul_f32 v[8:9], v[8:9], v[10:11]
	s_nop 0
	v_cvt_pk_bf16_f32 v7, v8, v9
	global_store_dwordx4 v[12:13], v[4:7], off
	s_nop 1
	v_or_b32_e32 v4, 24, v18
	v_mad_i64_i32 v[10:11], s[0:1], v4, s13, v[2:3]
	s_nop 0
	ds_read_b128 v[2:5], v0 offset:3456
	s_waitcnt lgkmcnt(0)
	v_lshlrev_b32_e32 v12, 16, v2
	v_and_b32_e32 v13, 0xffff0000, v2
	v_mov_b64_e32 v[6:7], v[142:143]
	v_mov_b64_e32 v[8:9], v[144:145]
	v_lshlrev_b32_e32 v14, 16, v6
	v_and_b32_e32 v15, 0xffff0000, v6
	v_pk_mul_f32 v[12:13], v[12:13], v[14:15]
	v_lshlrev_b32_e32 v6, 16, v7
	v_cvt_pk_bf16_f32 v2, v12, v13
	v_lshlrev_b32_e32 v12, 16, v3
	v_and_b32_e32 v13, 0xffff0000, v3
	v_and_b32_e32 v7, 0xffff0000, v7
	v_pk_mul_f32 v[6:7], v[12:13], v[6:7]
	v_lshlrev_b32_e32 v12, 16, v8
	v_cvt_pk_bf16_f32 v3, v6, v7
	v_lshlrev_b32_e32 v6, 16, v4
	v_and_b32_e32 v7, 0xffff0000, v4
	v_and_b32_e32 v13, 0xffff0000, v8
	v_pk_mul_f32 v[6:7], v[6:7], v[12:13]
	v_lshlrev_b32_e32 v8, 16, v9
	v_cvt_pk_bf16_f32 v4, v6, v7
	v_lshlrev_b32_e32 v6, 16, v5
	v_and_b32_e32 v7, 0xffff0000, v5
	v_and_b32_e32 v9, 0xffff0000, v9
	v_pk_mul_f32 v[6:7], v[6:7], v[8:9]
	s_nop 0
	v_cvt_pk_bf16_f32 v5, v6, v7
	global_store_dwordx4 v[10:11], v[2:5], off
.LBB0_782:
	v_readlane_b32 s0, v252, 0
	s_add_i32 s8, s8, s0
	s_cmp_lt_i32 s8, s69
	v_readlane_b32 s1, v252, 1
	s_cbranch_scc0 .LBB0_777
